# bundle: barrier invalidate behind the arrival atomics, in-proj tiles with no output skipped, SwiGLU epilogue constants folded into the row scale and shifts (one VALU op fewer per output)
# speedup vs baseline: 1.0076x; 1.0076x over previous
.LBB0_1125:
	s_lshl_b32 s12, s28, 8
	s_add_i32 s12, s12, s51
	v_or_b32_e32 v148, s12, v139
	v_ashrrev_i32_e32 v149, 31, v148
	v_lshl_add_u64 v[172:173], v[148:149], 2, s[8:9]
	global_load_dword v230, v[172:173], off
	global_load_dword v231, v[172:173], off offset:64
	global_load_dword v232, v[172:173], off offset:128
	global_load_dword v233, v[172:173], off offset:192
	global_load_dword v234, v[172:173], off offset:512
	global_load_dword v235, v[172:173], off offset:576
	global_load_dword v236, v[172:173], off offset:640
	global_load_dword v237, v[172:173], off offset:704
	s_ashr_i32 s13, s12, 13
	s_mul_i32 s40, s13, 0x1600
	s_lshl_b32 s36, s29, 8
	s_lshl_b32 s28, s29, 7
	s_ashr_i32 s41, s40, 31
	s_ashr_i32 s37, s36, 31
	s_ashr_i32 s29, s28, 31
	s_lshl_b64 s[40:41], s[40:41], 2
	s_add_u32 s13, s52, s40
	s_addc_u32 s21, s53, s41
	s_lshl_b64 s[36:37], s[36:37], 2
	s_add_u32 s40, s13, s36
	s_addc_u32 s41, s21, s37
	v_lshlrev_b32_e32 v149, 2, v138
	global_load_dwordx4 v[160:163], v149, s[40:41]
	global_load_dwordx4 v[156:159], v149, s[40:41] offset:512
	global_load_dwordx4 v[168:171], v149, s[40:41] offset:16
	global_load_dwordx4 v[164:167], v149, s[40:41] offset:528
	s_lshl_b64 s[28:29], s[28:29], 1
	s_mov_b32 s98, 0x16000
	s_mov_b32 s99, 0
	s_mov_b32 s100, 0x6e000
	s_mov_b32 s101, 0
	v_mov_b64_e32 v[174:175], s[92:93]
	v_lshlrev_b32_e32 v136, 1, v138
	v_mad_i64_i32 v[246:247], s[44:45], v148, s59, v[174:175]
	v_lshl_add_u64 v[246:247], v[246:247], 0, s[28:29]
	v_lshl_add_u64 v[246:247], v[246:247], 0, v[136:137]
	s_waitcnt vmcnt(0)
	v_fmamk_f32 v230, v230, 0x3a800000, v154
	v_fmamk_f32 v231, v231, 0x3a800000, v154
	v_fmamk_f32 v232, v232, 0x3a800000, v154
	v_fmamk_f32 v233, v233, 0x3a800000, v154
	v_fmamk_f32 v234, v234, 0x3a800000, v154
	v_fmamk_f32 v235, v235, 0x3a800000, v154
	v_fmamk_f32 v236, v236, 0x3a800000, v154
	v_fmamk_f32 v237, v237, 0x3a800000, v154
	v_rsq_f32_e32 v230, v230
	v_rsq_f32_e32 v231, v231
	v_rsq_f32_e32 v232, v232
	v_rsq_f32_e32 v233, v233
	v_rsq_f32_e32 v234, v234
	v_rsq_f32_e32 v235, v235
	v_rsq_f32_e32 v236, v236
	v_rsq_f32_e32 v237, v237
	s_mov_b32 s70, 0xbfb8aa3b
	s_mov_b32 s71, 0xbf317218
	v_mul_f32_e32 v160, s70, v160
	v_mul_f32_e32 v161, s70, v161
	v_mul_f32_e32 v162, s70, v162
	v_mul_f32_e32 v163, s70, v163
	v_mul_f32_e32 v168, s70, v168
	v_mul_f32_e32 v169, s70, v169
	v_mul_f32_e32 v170, s70, v170
	v_mul_f32_e32 v171, s70, v171
	v_mul_f32_e32 v156, s71, v156
	v_mul_f32_e32 v157, s71, v157
	v_mul_f32_e32 v158, s71, v158
	v_mul_f32_e32 v159, s71, v159
	v_mul_f32_e32 v164, s71, v164
	v_mul_f32_e32 v165, s71, v165
	v_mul_f32_e32 v166, s71, v166
	v_mul_f32_e32 v167, s71, v167
	v_mul_f32_e32 v248, s70, v230
	v_mul_f32_e32 v249, s71, v230
	v_fma_f32 v124, v124, v248, v160
	v_fma_f32 v125, v125, v248, v161
	v_fma_f32 v126, v126, v248, v162
	v_fma_f32 v127, v127, v248, v163
	v_fma_f32 v120, v120, v248, v168
	v_fma_f32 v121, v121, v248, v169
	v_fma_f32 v122, v122, v248, v170
	v_fma_f32 v123, v123, v248, v171
	v_exp_f32_e32 v238, v124
	v_exp_f32_e32 v239, v125
	v_exp_f32_e32 v240, v126
	v_exp_f32_e32 v241, v127
	v_exp_f32_e32 v242, v120
	v_exp_f32_e32 v243, v121
	v_exp_f32_e32 v244, v122
	v_exp_f32_e32 v245, v123
	v_fma_f32 v116, v116, v249, v156
	v_fma_f32 v117, v117, v249, v157
	v_fma_f32 v118, v118, v249, v158
	v_fma_f32 v119, v119, v249, v159
	v_fma_f32 v112, v112, v249, v164
	v_fma_f32 v113, v113, v249, v165
	v_fma_f32 v114, v114, v249, v166
	v_fma_f32 v115, v115, v249, v167
	v_add_f32_e32 v238, 1.0, v238
	v_add_f32_e32 v239, 1.0, v239
	v_add_f32_e32 v240, 1.0, v240
	v_add_f32_e32 v241, 1.0, v241
	v_add_f32_e32 v242, 1.0, v242
	v_add_f32_e32 v243, 1.0, v243
	v_add_f32_e32 v244, 1.0, v244
	v_add_f32_e32 v245, 1.0, v245
	v_rcp_f32_e32 v238, v238
	v_rcp_f32_e32 v239, v239
	v_rcp_f32_e32 v240, v240
	v_rcp_f32_e32 v241, v241
	v_rcp_f32_e32 v242, v242
	v_rcp_f32_e32 v243, v243
	v_rcp_f32_e32 v244, v244
	v_rcp_f32_e32 v245, v245
	v_mul_f32_e32 v124, v124, v116
	v_mul_f32_e32 v125, v125, v117
	v_mul_f32_e32 v126, v126, v118
	v_mul_f32_e32 v127, v127, v119
	v_mul_f32_e32 v120, v120, v112
	v_mul_f32_e32 v121, v121, v113
	v_mul_f32_e32 v122, v122, v114
	v_mul_f32_e32 v123, v123, v115
	v_mul_f32_e32 v124, v124, v238
	v_mul_f32_e32 v125, v125, v239
	v_mul_f32_e32 v126, v126, v240
	v_mul_f32_e32 v127, v127, v241
	v_mul_f32_e32 v120, v120, v242
	v_mul_f32_e32 v121, v121, v243
	v_mul_f32_e32 v122, v122, v244
	v_mul_f32_e32 v123, v123, v245
	v_cvt_pk_bf16_f32 v112, v124, v125
	v_cvt_pk_bf16_f32 v113, v126, v127
	v_cvt_pk_bf16_f32 v114, v120, v121
	v_cvt_pk_bf16_f32 v115, v122, v123
	global_store_dwordx4 v[246:247], v[112:115], off
	v_lshl_add_u64 v[246:247], v[246:247], 0, s[98:99]
	v_mul_f32_e32 v248, s70, v231
	v_mul_f32_e32 v249, s71, v231
	v_fma_f32 v108, v108, v248, v160
	v_fma_f32 v109, v109, v248, v161
	v_fma_f32 v110, v110, v248, v162
	v_fma_f32 v111, v111, v248, v163
	v_fma_f32 v104, v104, v248, v168
	v_fma_f32 v105, v105, v248, v169
	v_fma_f32 v106, v106, v248, v170
	v_fma_f32 v107, v107, v248, v171
	v_exp_f32_e32 v238, v108
	v_exp_f32_e32 v239, v109
	v_exp_f32_e32 v240, v110
	v_exp_f32_e32 v241, v111
	v_exp_f32_e32 v242, v104
	v_exp_f32_e32 v243, v105
	v_exp_f32_e32 v244, v106
	v_exp_f32_e32 v245, v107
	v_fma_f32 v100, v100, v249, v156
	v_fma_f32 v101, v101, v249, v157
	v_fma_f32 v102, v102, v249, v158
	v_fma_f32 v103, v103, v249, v159
	v_fma_f32 v96, v96, v249, v164
	v_fma_f32 v97, v97, v249, v165
	v_fma_f32 v98, v98, v249, v166
	v_fma_f32 v99, v99, v249, v167
	v_add_f32_e32 v238, 1.0, v238
	v_add_f32_e32 v239, 1.0, v239
	v_add_f32_e32 v240, 1.0, v240
	v_add_f32_e32 v241, 1.0, v241
	v_add_f32_e32 v242, 1.0, v242
	v_add_f32_e32 v243, 1.0, v243
	v_add_f32_e32 v244, 1.0, v244
	v_add_f32_e32 v245, 1.0, v245
	v_rcp_f32_e32 v238, v238
	v_rcp_f32_e32 v239, v239
	v_rcp_f32_e32 v240, v240
	v_rcp_f32_e32 v241, v241
	v_rcp_f32_e32 v242, v242
	v_rcp_f32_e32 v243, v243
	v_rcp_f32_e32 v244, v244
	v_rcp_f32_e32 v245, v245
	v_mul_f32_e32 v108, v108, v100
	v_mul_f32_e32 v109, v109, v101
	v_mul_f32_e32 v110, v110, v102
	v_mul_f32_e32 v111, v111, v103
	v_mul_f32_e32 v104, v104, v96
	v_mul_f32_e32 v105, v105, v97
	v_mul_f32_e32 v106, v106, v98
	v_mul_f32_e32 v107, v107, v99
	v_mul_f32_e32 v108, v108, v238
	v_mul_f32_e32 v109, v109, v239
	v_mul_f32_e32 v110, v110, v240
	v_mul_f32_e32 v111, v111, v241
	v_mul_f32_e32 v104, v104, v242
	v_mul_f32_e32 v105, v105, v243
	v_mul_f32_e32 v106, v106, v244
	v_mul_f32_e32 v107, v107, v245
	v_cvt_pk_bf16_f32 v96, v108, v109
	v_cvt_pk_bf16_f32 v97, v110, v111
	v_cvt_pk_bf16_f32 v98, v104, v105
	v_cvt_pk_bf16_f32 v99, v106, v107
	global_store_dwordx4 v[246:247], v[96:99], off
	v_lshl_add_u64 v[246:247], v[246:247], 0, s[98:99]
	v_mul_f32_e32 v248, s70, v232
	v_mul_f32_e32 v249, s71, v232
	v_fma_f32 v92, v92, v248, v160
	v_fma_f32 v93, v93, v248, v161
	v_fma_f32 v94, v94, v248, v162
	v_fma_f32 v95, v95, v248, v163
	v_fma_f32 v88, v88, v248, v168
	v_fma_f32 v89, v89, v248, v169
	v_fma_f32 v90, v90, v248, v170
	v_fma_f32 v91, v91, v248, v171
	v_exp_f32_e32 v238, v92
	v_exp_f32_e32 v239, v93
	v_exp_f32_e32 v240, v94
	v_exp_f32_e32 v241, v95
	v_exp_f32_e32 v242, v88
	v_exp_f32_e32 v243, v89
	v_exp_f32_e32 v244, v90
	v_exp_f32_e32 v245, v91
	v_fma_f32 v84, v84, v249, v156
	v_fma_f32 v85, v85, v249, v157
	v_fma_f32 v86, v86, v249, v158
	v_fma_f32 v87, v87, v249, v159
	v_fma_f32 v80, v80, v249, v164
	v_fma_f32 v81, v81, v249, v165
	v_fma_f32 v82, v82, v249, v166
	v_fma_f32 v83, v83, v249, v167
	v_add_f32_e32 v238, 1.0, v238
	v_add_f32_e32 v239, 1.0, v239
	v_add_f32_e32 v240, 1.0, v240
	v_add_f32_e32 v241, 1.0, v241
	v_add_f32_e32 v242, 1.0, v242
	v_add_f32_e32 v243, 1.0, v243
	v_add_f32_e32 v244, 1.0, v244
	v_add_f32_e32 v245, 1.0, v245
	v_rcp_f32_e32 v238, v238
	v_rcp_f32_e32 v239, v239
	v_rcp_f32_e32 v240, v240
	v_rcp_f32_e32 v241, v241
	v_rcp_f32_e32 v242, v242
	v_rcp_f32_e32 v243, v243
	v_rcp_f32_e32 v244, v244
	v_rcp_f32_e32 v245, v245
	v_mul_f32_e32 v92, v92, v84
	v_mul_f32_e32 v93, v93, v85
	v_mul_f32_e32 v94, v94, v86
	v_mul_f32_e32 v95, v95, v87
	v_mul_f32_e32 v88, v88, v80
	v_mul_f32_e32 v89, v89, v81
	v_mul_f32_e32 v90, v90, v82
	v_mul_f32_e32 v91, v91, v83
	v_mul_f32_e32 v92, v92, v238
	v_mul_f32_e32 v93, v93, v239
	v_mul_f32_e32 v94, v94, v240
	v_mul_f32_e32 v95, v95, v241
	v_mul_f32_e32 v88, v88, v242
	v_mul_f32_e32 v89, v89, v243
	v_mul_f32_e32 v90, v90, v244
	v_mul_f32_e32 v91, v91, v245
	v_cvt_pk_bf16_f32 v80, v92, v93
	v_cvt_pk_bf16_f32 v81, v94, v95
	v_cvt_pk_bf16_f32 v82, v88, v89
	v_cvt_pk_bf16_f32 v83, v90, v91
	global_store_dwordx4 v[246:247], v[80:83], off
	v_lshl_add_u64 v[246:247], v[246:247], 0, s[98:99]
	v_mul_f32_e32 v248, s70, v233
	v_mul_f32_e32 v249, s71, v233
	v_fma_f32 v76, v76, v248, v160
	v_fma_f32 v77, v77, v248, v161
	v_fma_f32 v78, v78, v248, v162
	v_fma_f32 v79, v79, v248, v163
	v_fma_f32 v72, v72, v248, v168
	v_fma_f32 v73, v73, v248, v169
	v_fma_f32 v74, v74, v248, v170
	v_fma_f32 v75, v75, v248, v171
	v_exp_f32_e32 v238, v76
	v_exp_f32_e32 v239, v77
	v_exp_f32_e32 v240, v78
	v_exp_f32_e32 v241, v79
	v_exp_f32_e32 v242, v72
	v_exp_f32_e32 v243, v73
	v_exp_f32_e32 v244, v74
	v_exp_f32_e32 v245, v75
	v_fma_f32 v68, v68, v249, v156
	v_fma_f32 v69, v69, v249, v157
	v_fma_f32 v70, v70, v249, v158
	v_fma_f32 v71, v71, v249, v159
	v_fma_f32 v64, v64, v249, v164
	v_fma_f32 v65, v65, v249, v165
	v_fma_f32 v66, v66, v249, v166
	v_fma_f32 v67, v67, v249, v167
	v_add_f32_e32 v238, 1.0, v238
	v_add_f32_e32 v239, 1.0, v239
	v_add_f32_e32 v240, 1.0, v240
	v_add_f32_e32 v241, 1.0, v241
	v_add_f32_e32 v242, 1.0, v242
	v_add_f32_e32 v243, 1.0, v243
	v_add_f32_e32 v244, 1.0, v244
	v_add_f32_e32 v245, 1.0, v245
	v_rcp_f32_e32 v238, v238
	v_rcp_f32_e32 v239, v239
	v_rcp_f32_e32 v240, v240
	v_rcp_f32_e32 v241, v241
	v_rcp_f32_e32 v242, v242
	v_rcp_f32_e32 v243, v243
	v_rcp_f32_e32 v244, v244
	v_rcp_f32_e32 v245, v245
	v_mul_f32_e32 v76, v76, v68
	v_mul_f32_e32 v77, v77, v69
	v_mul_f32_e32 v78, v78, v70
	v_mul_f32_e32 v79, v79, v71
	v_mul_f32_e32 v72, v72, v64
	v_mul_f32_e32 v73, v73, v65
	v_mul_f32_e32 v74, v74, v66
	v_mul_f32_e32 v75, v75, v67
	v_mul_f32_e32 v76, v76, v238
	v_mul_f32_e32 v77, v77, v239
	v_mul_f32_e32 v78, v78, v240
	v_mul_f32_e32 v79, v79, v241
	v_mul_f32_e32 v72, v72, v242
	v_mul_f32_e32 v73, v73, v243
	v_mul_f32_e32 v74, v74, v244
	v_mul_f32_e32 v75, v75, v245
	v_cvt_pk_bf16_f32 v64, v76, v77
	v_cvt_pk_bf16_f32 v65, v78, v79
	v_cvt_pk_bf16_f32 v66, v72, v73
	v_cvt_pk_bf16_f32 v67, v74, v75
	global_store_dwordx4 v[246:247], v[64:67], off
	v_lshl_add_u64 v[246:247], v[246:247], 0, s[100:101]
	v_mul_f32_e32 v248, s70, v234
	v_mul_f32_e32 v249, s71, v234
	v_fma_f32 v60, v60, v248, v160
	v_fma_f32 v61, v61, v248, v161
	v_fma_f32 v62, v62, v248, v162
	v_fma_f32 v63, v63, v248, v163
	v_fma_f32 v56, v56, v248, v168
	v_fma_f32 v57, v57, v248, v169
	v_fma_f32 v58, v58, v248, v170
	v_fma_f32 v59, v59, v248, v171
	v_exp_f32_e32 v238, v60
	v_exp_f32_e32 v239, v61
	v_exp_f32_e32 v240, v62
	v_exp_f32_e32 v241, v63
	v_exp_f32_e32 v242, v56
	v_exp_f32_e32 v243, v57
	v_exp_f32_e32 v244, v58
	v_exp_f32_e32 v245, v59
	v_fma_f32 v52, v52, v249, v156
	v_fma_f32 v53, v53, v249, v157
	v_fma_f32 v54, v54, v249, v158
	v_fma_f32 v55, v55, v249, v159
	v_fma_f32 v48, v48, v249, v164
	v_fma_f32 v49, v49, v249, v165
	v_fma_f32 v50, v50, v249, v166
	v_fma_f32 v51, v51, v249, v167
	v_add_f32_e32 v238, 1.0, v238
	v_add_f32_e32 v239, 1.0, v239
	v_add_f32_e32 v240, 1.0, v240
	v_add_f32_e32 v241, 1.0, v241
	v_add_f32_e32 v242, 1.0, v242
	v_add_f32_e32 v243, 1.0, v243
	v_add_f32_e32 v244, 1.0, v244
	v_add_f32_e32 v245, 1.0, v245
	v_rcp_f32_e32 v238, v238
	v_rcp_f32_e32 v239, v239
	v_rcp_f32_e32 v240, v240
	v_rcp_f32_e32 v241, v241
	v_rcp_f32_e32 v242, v242
	v_rcp_f32_e32 v243, v243
	v_rcp_f32_e32 v244, v244
	v_rcp_f32_e32 v245, v245
	v_mul_f32_e32 v60, v60, v52
	v_mul_f32_e32 v61, v61, v53
	v_mul_f32_e32 v62, v62, v54
	v_mul_f32_e32 v63, v63, v55
	v_mul_f32_e32 v56, v56, v48
	v_mul_f32_e32 v57, v57, v49
	v_mul_f32_e32 v58, v58, v50
	v_mul_f32_e32 v59, v59, v51
	v_mul_f32_e32 v60, v60, v238
	v_mul_f32_e32 v61, v61, v239
	v_mul_f32_e32 v62, v62, v240
	v_mul_f32_e32 v63, v63, v241
	v_mul_f32_e32 v56, v56, v242
	v_mul_f32_e32 v57, v57, v243
	v_mul_f32_e32 v58, v58, v244
	v_mul_f32_e32 v59, v59, v245
	v_cvt_pk_bf16_f32 v48, v60, v61
	v_cvt_pk_bf16_f32 v49, v62, v63
	v_cvt_pk_bf16_f32 v50, v56, v57
	v_cvt_pk_bf16_f32 v51, v58, v59
	global_store_dwordx4 v[246:247], v[48:51], off
	v_lshl_add_u64 v[246:247], v[246:247], 0, s[98:99]
	v_mul_f32_e32 v248, s70, v235
	v_mul_f32_e32 v249, s71, v235
	v_fma_f32 v44, v44, v248, v160
	v_fma_f32 v45, v45, v248, v161
	v_fma_f32 v46, v46, v248, v162
	v_fma_f32 v47, v47, v248, v163
	v_fma_f32 v40, v40, v248, v168
	v_fma_f32 v41, v41, v248, v169
	v_fma_f32 v42, v42, v248, v170
	v_fma_f32 v43, v43, v248, v171
	v_exp_f32_e32 v238, v44
	v_exp_f32_e32 v239, v45
	v_exp_f32_e32 v240, v46
	v_exp_f32_e32 v241, v47
	v_exp_f32_e32 v242, v40
	v_exp_f32_e32 v243, v41
	v_exp_f32_e32 v244, v42
	v_exp_f32_e32 v245, v43
	v_fma_f32 v36, v36, v249, v156
	v_fma_f32 v37, v37, v249, v157
	v_fma_f32 v38, v38, v249, v158
	v_fma_f32 v39, v39, v249, v159
	v_fma_f32 v32, v32, v249, v164
	v_fma_f32 v33, v33, v249, v165
	v_fma_f32 v34, v34, v249, v166
	v_fma_f32 v35, v35, v249, v167
	v_add_f32_e32 v238, 1.0, v238
	v_add_f32_e32 v239, 1.0, v239
	v_add_f32_e32 v240, 1.0, v240
	v_add_f32_e32 v241, 1.0, v241
	v_add_f32_e32 v242, 1.0, v242
	v_add_f32_e32 v243, 1.0, v243
	v_add_f32_e32 v244, 1.0, v244
	v_add_f32_e32 v245, 1.0, v245
	v_rcp_f32_e32 v238, v238
	v_rcp_f32_e32 v239, v239
	v_rcp_f32_e32 v240, v240
	v_rcp_f32_e32 v241, v241
	v_rcp_f32_e32 v242, v242
	v_rcp_f32_e32 v243, v243
	v_rcp_f32_e32 v244, v244
	v_rcp_f32_e32 v245, v245
	v_mul_f32_e32 v44, v44, v36
	v_mul_f32_e32 v45, v45, v37
	v_mul_f32_e32 v46, v46, v38
	v_mul_f32_e32 v47, v47, v39
	v_mul_f32_e32 v40, v40, v32
	v_mul_f32_e32 v41, v41, v33
	v_mul_f32_e32 v42, v42, v34
	v_mul_f32_e32 v43, v43, v35
	v_mul_f32_e32 v44, v44, v238
	v_mul_f32_e32 v45, v45, v239
	v_mul_f32_e32 v46, v46, v240
	v_mul_f32_e32 v47, v47, v241
	v_mul_f32_e32 v40, v40, v242
	v_mul_f32_e32 v41, v41, v243
	v_mul_f32_e32 v42, v42, v244
	v_mul_f32_e32 v43, v43, v245
	v_cvt_pk_bf16_f32 v32, v44, v45
	v_cvt_pk_bf16_f32 v33, v46, v47
	v_cvt_pk_bf16_f32 v34, v40, v41
	v_cvt_pk_bf16_f32 v35, v42, v43
	global_store_dwordx4 v[246:247], v[32:35], off
	v_lshl_add_u64 v[246:247], v[246:247], 0, s[98:99]
	v_mul_f32_e32 v248, s70, v236
	v_mul_f32_e32 v249, s71, v236
	v_fma_f32 v28, v28, v248, v160
	v_fma_f32 v29, v29, v248, v161
	v_fma_f32 v30, v30, v248, v162
	v_fma_f32 v31, v31, v248, v163
	v_fma_f32 v24, v24, v248, v168
	v_fma_f32 v25, v25, v248, v169
	v_fma_f32 v26, v26, v248, v170
	v_fma_f32 v27, v27, v248, v171
	v_exp_f32_e32 v238, v28
	v_exp_f32_e32 v239, v29
	v_exp_f32_e32 v240, v30
	v_exp_f32_e32 v241, v31
	v_exp_f32_e32 v242, v24
	v_exp_f32_e32 v243, v25
	v_exp_f32_e32 v244, v26
	v_exp_f32_e32 v245, v27
	v_fma_f32 v20, v20, v249, v156
	v_fma_f32 v21, v21, v249, v157
	v_fma_f32 v22, v22, v249, v158
	v_fma_f32 v23, v23, v249, v159
	v_fma_f32 v16, v16, v249, v164
	v_fma_f32 v17, v17, v249, v165
	v_fma_f32 v18, v18, v249, v166
	v_fma_f32 v19, v19, v249, v167
	v_add_f32_e32 v238, 1.0, v238
	v_add_f32_e32 v239, 1.0, v239
	v_add_f32_e32 v240, 1.0, v240
	v_add_f32_e32 v241, 1.0, v241
	v_add_f32_e32 v242, 1.0, v242
	v_add_f32_e32 v243, 1.0, v243
	v_add_f32_e32 v244, 1.0, v244
	v_add_f32_e32 v245, 1.0, v245
	v_rcp_f32_e32 v238, v238
	v_rcp_f32_e32 v239, v239
	v_rcp_f32_e32 v240, v240
	v_rcp_f32_e32 v241, v241
	v_rcp_f32_e32 v242, v242
	v_rcp_f32_e32 v243, v243
	v_rcp_f32_e32 v244, v244
	v_rcp_f32_e32 v245, v245
	v_mul_f32_e32 v28, v28, v20
	v_mul_f32_e32 v29, v29, v21
	v_mul_f32_e32 v30, v30, v22
	v_mul_f32_e32 v31, v31, v23
	v_mul_f32_e32 v24, v24, v16
	v_mul_f32_e32 v25, v25, v17
	v_mul_f32_e32 v26, v26, v18
	v_mul_f32_e32 v27, v27, v19
	v_mul_f32_e32 v28, v28, v238
	v_mul_f32_e32 v29, v29, v239
	v_mul_f32_e32 v30, v30, v240
	v_mul_f32_e32 v31, v31, v241
	v_mul_f32_e32 v24, v24, v242
	v_mul_f32_e32 v25, v25, v243
	v_mul_f32_e32 v26, v26, v244
	v_mul_f32_e32 v27, v27, v245
	v_cvt_pk_bf16_f32 v16, v28, v29
	v_cvt_pk_bf16_f32 v17, v30, v31
	v_cvt_pk_bf16_f32 v18, v24, v25
	v_cvt_pk_bf16_f32 v19, v26, v27
	global_store_dwordx4 v[246:247], v[16:19], off
	v_lshl_add_u64 v[246:247], v[246:247], 0, s[98:99]
	v_mul_f32_e32 v248, s70, v237
	v_mul_f32_e32 v249, s71, v237
	v_fma_f32 v12, v12, v248, v160
	v_fma_f32 v13, v13, v248, v161
	v_fma_f32 v14, v14, v248, v162
	v_fma_f32 v15, v15, v248, v163
	v_fma_f32 v8, v8, v248, v168
	v_fma_f32 v9, v9, v248, v169
	v_fma_f32 v10, v10, v248, v170
	v_fma_f32 v11, v11, v248, v171
	v_exp_f32_e32 v238, v12
	v_exp_f32_e32 v239, v13
	v_exp_f32_e32 v240, v14
	v_exp_f32_e32 v241, v15
	v_exp_f32_e32 v242, v8
	v_exp_f32_e32 v243, v9
	v_exp_f32_e32 v244, v10
	v_exp_f32_e32 v245, v11
	v_fma_f32 v4, v4, v249, v156
	v_fma_f32 v5, v5, v249, v157
	v_fma_f32 v6, v6, v249, v158
	v_fma_f32 v7, v7, v249, v159
	v_fma_f32 v0, v0, v249, v164
	v_fma_f32 v1, v1, v249, v165
	v_fma_f32 v2, v2, v249, v166
	v_fma_f32 v3, v3, v249, v167
	v_add_f32_e32 v238, 1.0, v238
	v_add_f32_e32 v239, 1.0, v239
	v_add_f32_e32 v240, 1.0, v240
	v_add_f32_e32 v241, 1.0, v241
	v_add_f32_e32 v242, 1.0, v242
	v_add_f32_e32 v243, 1.0, v243
	v_add_f32_e32 v244, 1.0, v244
	v_add_f32_e32 v245, 1.0, v245
	v_rcp_f32_e32 v238, v238
	v_rcp_f32_e32 v239, v239
	v_rcp_f32_e32 v240, v240
	v_rcp_f32_e32 v241, v241
	v_rcp_f32_e32 v242, v242
	v_rcp_f32_e32 v243, v243
	v_rcp_f32_e32 v244, v244
	v_rcp_f32_e32 v245, v245
	v_mul_f32_e32 v12, v12, v4
	v_mul_f32_e32 v13, v13, v5
	v_mul_f32_e32 v14, v14, v6
	v_mul_f32_e32 v15, v15, v7
	v_mul_f32_e32 v8, v8, v0
	v_mul_f32_e32 v9, v9, v1
	v_mul_f32_e32 v10, v10, v2
	v_mul_f32_e32 v11, v11, v3
	v_mul_f32_e32 v12, v12, v238
	v_mul_f32_e32 v13, v13, v239
	v_mul_f32_e32 v14, v14, v240
	v_mul_f32_e32 v15, v15, v241
	v_mul_f32_e32 v8, v8, v242
	v_mul_f32_e32 v9, v9, v243
	v_mul_f32_e32 v10, v10, v244
	v_mul_f32_e32 v11, v11, v245
	v_cvt_pk_bf16_f32 v0, v12, v13
	v_cvt_pk_bf16_f32 v1, v14, v15
	v_cvt_pk_bf16_f32 v2, v8, v9
	v_cvt_pk_bf16_f32 v3, v10, v11
	s_andn2_b64 vcc, exec, s[0:1]
	s_mov_b64 s[0:1], -1
	global_store_dwordx4 v[246:247], v[0:3], off
	s_cbranch_vccnz .LBB0_1118
	s_andn2_b64 vcc, exec, s[10:11]
	s_cbranch_vccnz .LBB0_1117
	s_barrier
	s_branch .LBB0_1117
